# same as best but without the in-proj L0 free-slack start delay (sensitivity check with rotated-K feed)
# baseline (speedup 1.0000x reference)
; DI int tidx() { int t = threadIdx.x; asm volatile("" : "+v"(t)); return t; }
; template <int EPI>
; DI void gemm_phase(const P& p, int l, const u16* __restrict__ A, const u16* __restrict__ Bt, int mpx, char* lds) {
;   const int tid = tidx();
;   int t = 0;
;   int m0, n0;
;   if (!tile_coords<EPI>(t, mpx, m0, n0)) return;
;   const unsigned voffb = (unsigned)(((tid >> 3) * 1024 + (tid & 7) * 8) * 2);
;   const u16* Ag = A + (size_t)m0 * 1024;
;   const u16* Bg = Bt + (size_t)n0 * 1024;
; __global__ void __launch_bounds__(512, 2) mega(P p) {
;     ...
;       const int l = (ph - 2) >> 2, s = (ph - 2) & 3;
;       if (s == 0) { for (int rr = 0; rr < REP_INPROJ; ++rr) { if (rr) cg::this_grid().sync(); phase_inproj(p, l, lds); } }
.LBB0_74:
	s_andn2_b64 vcc, exec, s[0:1]
	s_cbranch_vccnz .LBB0_941
	s_cmp_lg_u32 s24, 1
	s_mov_b64 s[0:1], -1
	s_cbranch_scc0 .LBB0_812
	v_readlane_b32 s0, v254, 9
	v_readlane_b32 s1, v254, 10
	v_mov_b32_e32 v0, v195
	s_andn2_b64 vcc, exec, s[0:1]
	s_cbranch_vccnz .LBB0_811
	s_cmp_lg_u32 s50, 0
	s_cbranch_scc1 .Ldephase_in_done
	s_cmp_lt_u32 s84, 14
	s_cbranch_scc1 .Ldephase_in_done
.Ldephase_in_done:
	s_cmp_lg_u32 s50, 1
	s_cbranch_scc1 .Ltile_fix_done
	v_readlane_b32 s42, v254, 11
	s_lshl_b32 s43, s42, 20
	s_lshl_b32 s42, s42, 9
	v_readlane_b32 s40, v254, 58
	s_sub_i32 s40, s40, s42
	s_nop 1
	v_writelane_b32 v254, s40, 58
	v_readlane_b32 s40, v254, 61
	v_readlane_b32 s41, v254, 62
	s_sub_u32 s40, s40, s43
	s_subb_u32 s41, s41, 0
	s_nop 1
	v_writelane_b32 v254, s40, 61
	v_writelane_b32 v254, s41, 62
	v_readlane_b32 s40, v254, 63
	v_readlane_b32 s41, v255, 0
	s_sub_u32 s40, s40, s43
	s_subb_u32 s41, s41, 0
	s_nop 1
	v_writelane_b32 v254, s40, 63
	v_writelane_b32 v255, s41, 0
	v_readlane_b32 s40, v255, 1
	v_readlane_b32 s41, v255, 2
	s_sub_u32 s40, s40, s43
	s_subb_u32 s41, s41, 0
	s_nop 1
	v_writelane_b32 v255, s40, 1
	v_writelane_b32 v255, s41, 2
	v_readlane_b32 s40, v255, 3
	v_readlane_b32 s41, v255, 4
	s_sub_u32 s40, s40, s43
	s_subb_u32 s41, s41, 0
	s_nop 1
	v_writelane_b32 v255, s40, 3
	v_writelane_b32 v255, s41, 4
